# gdn_prep forward substitution: LDS read groups of the inner loops issued early into free VGPRs with counted lgkmcnt waits (5 -> 2 exposed round trips per unrolled iteration); on top of v88
# speedup vs baseline: 1.0072x; 1.0025x over previous
.LBB0_600:
	ds_read2_b32 v[56:57], v26 offset1:68
	ds_read2_b32 v[58:59], v26 offset0:136 offset1:204
	ds_read_b128 v[4:7], v27
	ds_read_b128 v[28:31], v27 offset:16
	ds_read_b128 v[12:15], v27 offset:32
	ds_read_b128 v[0:3], v27 offset:48
	ds_read_b128 v[8:11], v27 offset:272
	ds_read_b128 v[98:101], v24
	ds_read_b128 v[102:105], v24 offset:16
	ds_read_b128 v[106:109], v24 offset:32
	ds_read_b128 v[110:113], v24 offset:48
	ds_read_b128 v[114:117], v25
	ds_read_b128 v[118:121], v25 offset:16
	ds_read_b128 v[122:125], v25 offset:32
	ds_read_b128 v[126:129], v25 offset:48
	s_waitcnt lgkmcnt(12)
	v_mov_b32_e32 v33, v4
	v_mov_b32_e32 v60, v57
	v_mov_b32_e32 v62, v59
	s_add_i32 s48, s48, 16
	s_waitcnt lgkmcnt(8)
	v_mov_b32_e32 v4, v9
	v_mov_b32_e32 v32, v8
	v_pk_mul_f32 v[4:5], v[60:61], v[4:5] op_sel_hi:[0,1]
	v_pk_fma_f32 v[4:5], v[56:57], v[32:33], v[4:5] op_sel_hi:[0,1,1]
	v_mov_b32_e32 v8, v10
	v_mov_b32_e32 v9, v6
	v_pk_fma_f32 v[4:5], v[58:59], v[8:9], v[4:5] op_sel_hi:[0,1,1]
	v_mov_b32_e32 v6, v11
	v_pk_fma_f32 v[4:5], v[62:63], v[6:7], v[4:5] op_sel_hi:[0,1,1]
	v_pk_add_f32 v[64:65], v[22:23], v[4:5] neg_lo:[0,1] neg_hi:[0,1]
	s_waitcnt lgkmcnt(6)
	v_add_u32_e32 v154, 0x400, v26
	v_add_u32_e32 v155, 0x800, v26
	v_add_u32_e32 v156, 0xc00, v26
	ds_read2_b32 v[130:131], v154 offset0:16 offset1:84
	ds_read2_b32 v[132:133], v154 offset0:152 offset1:220
	ds_read_b128 v[134:137], v27 offset:288
	ds_read2_b32 v[138:139], v155 offset0:32 offset1:100
	ds_read2_b32 v[140:141], v155 offset0:168 offset1:236
	ds_read_b128 v[142:145], v27 offset:304
	ds_read2_b32 v[146:147], v156 offset0:48 offset1:116
	ds_read2_b32 v[148:149], v156 offset0:184 offset1:252
	ds_read_b128 v[150:153], v27 offset:320
	s_waitcnt lgkmcnt(15)
	v_mov_b32_e32 v23, v98
	s_waitcnt lgkmcnt(12)
	v_mov_b32_e32 v32, v115
	v_mov_b32_e32 v22, v114
	v_mov_b32_e32 v33, v99
	v_pk_mul_f32 v[32:33], v[60:61], v[32:33] op_sel_hi:[0,1]
	v_pk_fma_f32 v[22:23], v[56:57], v[22:23], v[32:33] op_sel_hi:[0,1,1]
	v_mov_b32_e32 v32, v116
	v_mov_b32_e32 v33, v100
	v_pk_fma_f32 v[22:23], v[58:59], v[32:33], v[22:23] op_sel_hi:[0,1,1]
	v_mov_b32_e32 v34, v117
	v_mov_b32_e32 v35, v101
	v_pk_fma_f32 v[22:23], v[62:63], v[34:35], v[22:23] op_sel_hi:[0,1,1]
	v_pk_add_f32 v[32:33], v[20:21], v[22:23] neg_lo:[0,1] neg_hi:[0,1]
	v_mov_b32_e32 v47, v28
	s_add_i32 s49, s49, -4
	v_add_u32_e32 v25, 64, v25
	v_add_u32_e32 v24, 64, v24
	s_waitcnt lgkmcnt(6)
	v_mov_b32_e32 v46, v134
	v_mov_b32_e32 v20, v131
	v_mov_b32_e32 v28, v135
	v_mov_b32_e32 v21, v135
	v_pk_mul_f32 v[28:29], v[20:21], v[28:29] op_sel_hi:[0,1]
	v_pk_fma_f32 v[28:29], v[130:131], v[46:47], v[28:29] op_sel_hi:[0,1,1]
	v_mov_b32_e32 v46, v136
	v_mov_b32_e32 v47, v30
	v_pk_fma_f32 v[28:29], v[132:133], v[46:47], v[28:29] op_sel_hi:[0,1,1]
	v_mov_b32_e32 v22, v133
	v_mov_b32_e32 v30, v137
	v_mov_b32_e32 v23, v137
	v_pk_fma_f32 v[28:29], v[22:23], v[30:31], v[28:29] op_sel_hi:[0,1,1]
	v_mov_b32_e32 v31, v102
	v_mov_b32_e32 v36, v119
	v_mov_b32_e32 v30, v118
	v_mov_b32_e32 v37, v103
	v_pk_mul_f32 v[20:21], v[20:21], v[36:37] op_sel_hi:[0,1]
	v_pk_fma_f32 v[20:21], v[130:131], v[30:31], v[20:21] op_sel_hi:[0,1,1]
	v_mov_b32_e32 v30, v120
	v_mov_b32_e32 v31, v104
	v_pk_fma_f32 v[20:21], v[132:133], v[30:31], v[20:21] op_sel_hi:[0,1,1]
	v_mov_b32_e32 v38, v121
	v_mov_b32_e32 v39, v105
	v_pk_fma_f32 v[20:21], v[22:23], v[38:39], v[20:21] op_sel_hi:[0,1,1]
	v_pk_add_f32 v[30:31], v[32:33], v[20:21] neg_lo:[0,1] neg_hi:[0,1]
	v_mov_b32_e32 v37, v12
	v_pk_add_f32 v[28:29], v[64:65], v[28:29] neg_lo:[0,1] neg_hi:[0,1]
	s_cmp_eq_u32 s49, 0
	s_waitcnt lgkmcnt(3)
	v_mov_b32_e32 v36, v142
	v_mov_b32_e32 v20, v139
	v_mov_b32_e32 v12, v143
	v_mov_b32_e32 v21, v143
	v_pk_mul_f32 v[12:13], v[20:21], v[12:13] op_sel_hi:[0,1]
	v_pk_fma_f32 v[12:13], v[138:139], v[36:37], v[12:13] op_sel_hi:[0,1,1]
	v_mov_b32_e32 v36, v144
	v_mov_b32_e32 v37, v14
	v_pk_fma_f32 v[12:13], v[140:141], v[36:37], v[12:13] op_sel_hi:[0,1,1]
	v_mov_b32_e32 v22, v141
	v_mov_b32_e32 v14, v145
	v_mov_b32_e32 v23, v145
	v_pk_fma_f32 v[12:13], v[22:23], v[14:15], v[12:13] op_sel_hi:[0,1,1]
	v_pk_add_f32 v[28:29], v[28:29], v[12:13] neg_lo:[0,1] neg_hi:[0,1]
	v_mov_b32_e32 v13, v106
	v_mov_b32_e32 v40, v123
	v_mov_b32_e32 v12, v122
	v_mov_b32_e32 v41, v107
	v_pk_mul_f32 v[14:15], v[20:21], v[40:41] op_sel_hi:[0,1]
	v_pk_fma_f32 v[12:13], v[138:139], v[12:13], v[14:15] op_sel_hi:[0,1,1]
	v_mov_b32_e32 v14, v124
	v_mov_b32_e32 v15, v108
	v_pk_fma_f32 v[12:13], v[140:141], v[14:15], v[12:13] op_sel_hi:[0,1,1]
	v_mov_b32_e32 v42, v125
	v_mov_b32_e32 v43, v109
	v_pk_fma_f32 v[12:13], v[22:23], v[42:43], v[12:13] op_sel_hi:[0,1,1]
	v_pk_add_f32 v[20:21], v[30:31], v[12:13] neg_lo:[0,1] neg_hi:[0,1]
	v_mov_b32_e32 v23, v0
	v_add_u32_e32 v27, 64, v27
	v_add_u32_e32 v26, 0x1100, v26
	s_waitcnt lgkmcnt(0)
	v_mov_b32_e32 v22, v150
	v_mov_b32_e32 v12, v147
	v_mov_b32_e32 v0, v151
	v_mov_b32_e32 v13, v151
	v_pk_mul_f32 v[0:1], v[12:13], v[0:1] op_sel_hi:[0,1]
	v_pk_fma_f32 v[0:1], v[146:147], v[22:23], v[0:1] op_sel_hi:[0,1,1]
	v_mov_b32_e32 v22, v152
	v_mov_b32_e32 v23, v2
	v_pk_fma_f32 v[0:1], v[148:149], v[22:23], v[0:1] op_sel_hi:[0,1,1]
	v_mov_b32_e32 v14, v149
	v_mov_b32_e32 v2, v153
	v_mov_b32_e32 v15, v153
	v_pk_fma_f32 v[0:1], v[14:15], v[2:3], v[0:1] op_sel_hi:[0,1,1]
	v_pk_add_f32 v[22:23], v[28:29], v[0:1] neg_lo:[0,1] neg_hi:[0,1]
	v_mov_b32_e32 v1, v110
	v_mov_b32_e32 v4, v127
	v_mov_b32_e32 v0, v126
	v_mov_b32_e32 v5, v111
	v_pk_mul_f32 v[2:3], v[12:13], v[4:5] op_sel_hi:[0,1]
	v_pk_fma_f32 v[0:1], v[146:147], v[0:1], v[2:3] op_sel_hi:[0,1,1]
	v_mov_b32_e32 v2, v128
	v_mov_b32_e32 v3, v112
	v_pk_fma_f32 v[0:1], v[148:149], v[2:3], v[0:1] op_sel_hi:[0,1,1]
	v_mov_b32_e32 v6, v129
	v_mov_b32_e32 v7, v113
	v_pk_fma_f32 v[0:1], v[14:15], v[6:7], v[0:1] op_sel_hi:[0,1,1]
	v_pk_add_f32 v[20:21], v[20:21], v[0:1] neg_lo:[0,1] neg_hi:[0,1]
	s_cbranch_scc0 .LBB0_600

.LBB0_603:
	v_add_u32_e32 v8, s44, v3
	ds_read2_b32 v[12:13], v2 offset1:68
	ds_read2_b32 v[14:15], v2 offset0:136 offset1:204
	ds_read_b128 v[4:7], v8
	ds_read_b128 v[8:11], v8 offset:272
	v_add_u32_e32 v27, s44, v1
	v_add_u32_e32 v28, s44, v0
	ds_read_b128 v[158:161], v27
	ds_read_b128 v[162:165], v28
	s_waitcnt lgkmcnt(5)
	v_mov_b32_e32 v26, v13
	s_waitcnt lgkmcnt(3)
	v_mov_b32_e32 v25, v4
	s_waitcnt lgkmcnt(2)
	v_mov_b32_e32 v4, v9
	v_mov_b32_e32 v24, v8
	v_pk_mul_f32 v[4:5], v[26:27], v[4:5] op_sel_hi:[0,1]
	v_pk_fma_f32 v[4:5], v[12:13], v[24:25], v[4:5] op_sel_hi:[0,1,1]
	v_mov_b32_e32 v8, v10
	v_mov_b32_e32 v9, v6
	v_pk_fma_f32 v[4:5], v[14:15], v[8:9], v[4:5] op_sel_hi:[0,1,1]
	v_mov_b32_e32 v24, v15
	v_mov_b32_e32 v6, v11
	v_pk_fma_f32 v[4:5], v[24:25], v[6:7], v[4:5] op_sel_hi:[0,1,1]
	v_pk_add_f32 v[22:23], v[22:23], v[4:5] neg_lo:[0,1] neg_hi:[0,1]
	s_add_i32 s44, s44, 16
	v_add_u32_e32 v2, 0x440, v2
	s_cmp_lg_u32 s46, s44
	s_waitcnt lgkmcnt(1)
	v_mov_b32_e32 v29, v158
	s_waitcnt lgkmcnt(0)
	v_mov_b32_e32 v4, v163
	v_mov_b32_e32 v28, v162
	v_mov_b32_e32 v5, v159
	v_pk_mul_f32 v[4:5], v[26:27], v[4:5] op_sel_hi:[0,1]
	v_pk_fma_f32 v[4:5], v[12:13], v[28:29], v[4:5] op_sel_hi:[0,1,1]
	v_mov_b32_e32 v8, v164
	v_mov_b32_e32 v9, v160
	v_pk_fma_f32 v[4:5], v[14:15], v[8:9], v[4:5] op_sel_hi:[0,1,1]
	v_mov_b32_e32 v6, v165
	v_mov_b32_e32 v7, v161
	v_pk_fma_f32 v[4:5], v[24:25], v[6:7], v[4:5] op_sel_hi:[0,1,1]
	v_pk_add_f32 v[20:21], v[20:21], v[4:5] neg_lo:[0,1] neg_hi:[0,1]
	s_cbranch_scc1 .LBB0_603
